# GEMM loops: vmcnt(0) moved from before ds_reads to before end-of-iteration barrier
# speedup vs baseline: 1.0415x; 1.0415x over previous
.LBB0_713:
	s_and_b32 s16, s7, 1
	s_xor_b32 s17, s16, 1
	s_lshl_b32 s33, s17, 14
	v_lshl_add_u64 v[150:151], v[146:147], 0, s[14:15]
	s_add_i32 s33, s1, s33
	v_lshl_add_u64 v[178:179], v[150:151], 0, 64
	s_mov_b32 m0, s33
	v_lshl_add_u64 v[180:181], v[150:151], 0, s[38:39]
	global_load_lds_dwordx4 v[178:179], off
	s_add_i32 m0, s33, 0x400
	v_lshl_add_u64 v[182:183], v[150:151], 0, s[40:41]
	s_lshl_b32 s17, s17, 13
	global_load_lds_dwordx4 v[180:181], off
	s_add_i32 m0, s33, 0x800
	v_lshl_add_u64 v[172:173], v[148:149], 0, s[14:15]
	v_lshl_add_u64 v[150:151], v[150:151], 0, s[42:43]
	s_add_i32 s17, s6, s17
	global_load_lds_dwordx4 v[182:183], off
	s_add_i32 m0, s33, 0xc00
	v_lshl_add_u64 v[184:185], v[172:173], 0, 64
	global_load_lds_dwordx4 v[150:151], off
	s_add_i32 m0, s17, 0x8000
	v_lshl_add_u64 v[172:173], v[172:173], 0, s[38:39]
	global_load_lds_dwordx4 v[184:185], off
	s_add_i32 m0, s17, 0x8400
	v_lshl_or_b32 v145, s16, 13, v136
	global_load_lds_dwordx4 v[172:173], off
	v_lshl_add_u32 v150, s16, 14, v143
	ds_read_b128 v[178:181], v145 offset:32768
	ds_read_b128 v[182:185], v145 offset:33792
	ds_read_b128 v[186:189], v145 offset:34816
	ds_read_b128 v[190:193], v145 offset:35840
	ds_read_b128 v[194:197], v150
	ds_read_b128 v[198:201], v150 offset:1024
	ds_read_b128 v[202:205], v150 offset:2048
	ds_read_b128 v[206:209], v150 offset:3072
	ds_read_b128 v[210:213], v150 offset:4096
	ds_read_b128 v[214:217], v150 offset:5120
	ds_read_b128 v[218:221], v150 offset:6144
	ds_read_b128 v[222:225], v150 offset:7168
	s_add_i32 s7, s7, 1
	s_setprio 1
	s_waitcnt lgkmcnt(0)
	v_mfma_f32_16x16x32_bf16 v[28:31], v[178:181], v[194:197], v[28:31]
	v_mfma_f32_16x16x32_bf16 v[24:27], v[178:181], v[198:201], v[24:27]
	v_mfma_f32_16x16x32_bf16 v[20:23], v[178:181], v[202:205], v[20:23]
	v_mfma_f32_16x16x32_bf16 v[16:19], v[178:181], v[206:209], v[16:19]
	v_mfma_f32_16x16x32_bf16 v[12:15], v[178:181], v[210:213], v[12:15]
	v_mfma_f32_16x16x32_bf16 v[8:11], v[178:181], v[214:217], v[8:11]
	v_mfma_f32_16x16x32_bf16 v[4:7], v[178:181], v[218:221], v[4:7]
	v_mfma_f32_16x16x32_bf16 v[0:3], v[178:181], v[222:225], v[0:3]
	v_mfma_f32_16x16x32_bf16 v[124:127], v[182:185], v[194:197], v[124:127]
	v_mfma_f32_16x16x32_bf16 v[120:123], v[182:185], v[198:201], v[120:123]
	v_mfma_f32_16x16x32_bf16 v[116:119], v[182:185], v[202:205], v[116:119]
	v_mfma_f32_16x16x32_bf16 v[80:83], v[182:185], v[206:209], v[80:83]
	v_mfma_f32_16x16x32_bf16 v[68:71], v[182:185], v[210:213], v[68:71]
	v_mfma_f32_16x16x32_bf16 v[56:59], v[182:185], v[214:217], v[56:59]
	v_mfma_f32_16x16x32_bf16 v[44:47], v[182:185], v[218:221], v[44:47]
	v_mfma_f32_16x16x32_bf16 v[32:35], v[182:185], v[222:225], v[32:35]
	v_mfma_f32_16x16x32_bf16 v[112:115], v[186:189], v[194:197], v[112:115]
	v_mfma_f32_16x16x32_bf16 v[108:111], v[186:189], v[198:201], v[108:111]
	v_mfma_f32_16x16x32_bf16 v[104:107], v[186:189], v[202:205], v[104:107]
	v_mfma_f32_16x16x32_bf16 v[84:87], v[186:189], v[206:209], v[84:87]
	v_mfma_f32_16x16x32_bf16 v[72:75], v[186:189], v[210:213], v[72:75]
	v_mfma_f32_16x16x32_bf16 v[60:63], v[186:189], v[214:217], v[60:63]
	v_mfma_f32_16x16x32_bf16 v[48:51], v[186:189], v[218:221], v[48:51]
	v_mfma_f32_16x16x32_bf16 v[36:39], v[186:189], v[222:225], v[36:39]
	v_mfma_f32_16x16x32_bf16 v[100:103], v[190:193], v[194:197], v[100:103]
	v_mfma_f32_16x16x32_bf16 v[96:99], v[190:193], v[198:201], v[96:99]
	v_mfma_f32_16x16x32_bf16 v[92:95], v[190:193], v[202:205], v[92:95]
	v_mfma_f32_16x16x32_bf16 v[88:91], v[190:193], v[206:209], v[88:91]
	v_mfma_f32_16x16x32_bf16 v[76:79], v[190:193], v[210:213], v[76:79]
	v_mfma_f32_16x16x32_bf16 v[64:67], v[190:193], v[214:217], v[64:67]
	v_mfma_f32_16x16x32_bf16 v[52:55], v[190:193], v[218:221], v[52:55]
	v_mfma_f32_16x16x32_bf16 v[40:43], v[190:193], v[222:225], v[40:43]
	s_setprio 0
	s_add_u32 s14, s14, 64
	s_addc_u32 s15, s15, 0
	s_cmpk_eq_i32 s14, 0xfc0
	s_waitcnt vmcnt(0)
	s_barrier
	s_cbranch_scc0 .LBB0_713
	ds_read_b128 v[146:149], v143 offset:23552
	ds_read_b128 v[178:181], v143 offset:22528
	ds_read_b128 v[182:185], v143 offset:21504
	ds_read_b128 v[186:189], v143 offset:20480
	ds_read_b128 v[190:193], v143 offset:19456
	ds_read_b128 v[194:197], v143 offset:18432
	ds_read_b128 v[198:201], v143 offset:17408
	ds_read_b128 v[202:205], v143 offset:16384
	ds_read_b128 v[206:209], v136 offset:44032
	ds_read_b128 v[210:213], v136 offset:43008
	ds_read_b128 v[214:217], v136 offset:41984
	ds_read_b128 v[218:221], v136 offset:40960
	s_setprio 1
	s_waitcnt lgkmcnt(0)
	v_mfma_f32_16x16x32_bf16 v[28:31], v[218:221], v[202:205], v[28:31]
	v_mfma_f32_16x16x32_bf16 v[24:27], v[218:221], v[198:201], v[24:27]
	v_mfma_f32_16x16x32_bf16 v[20:23], v[218:221], v[194:197], v[20:23]
	v_mfma_f32_16x16x32_bf16 v[16:19], v[218:221], v[190:193], v[16:19]
	v_mfma_f32_16x16x32_bf16 v[12:15], v[218:221], v[186:189], v[12:15]
	v_mfma_f32_16x16x32_bf16 v[8:11], v[218:221], v[182:185], v[8:11]
	v_mfma_f32_16x16x32_bf16 v[4:7], v[218:221], v[178:181], v[4:7]
	v_mfma_f32_16x16x32_bf16 v[0:3], v[218:221], v[146:149], v[0:3]
	v_mfma_f32_16x16x32_bf16 v[124:127], v[214:217], v[202:205], v[124:127]
	v_mfma_f32_16x16x32_bf16 v[120:123], v[214:217], v[198:201], v[120:123]
	v_mfma_f32_16x16x32_bf16 v[116:119], v[214:217], v[194:197], v[116:119]
	v_mfma_f32_16x16x32_bf16 v[80:83], v[214:217], v[190:193], v[80:83]
	v_mfma_f32_16x16x32_bf16 v[68:71], v[214:217], v[186:189], v[68:71]
	v_mfma_f32_16x16x32_bf16 v[56:59], v[214:217], v[182:185], v[56:59]
	v_mfma_f32_16x16x32_bf16 v[44:47], v[214:217], v[178:181], v[44:47]
	v_mfma_f32_16x16x32_bf16 v[32:35], v[214:217], v[146:149], v[32:35]
	v_mfma_f32_16x16x32_bf16 v[112:115], v[210:213], v[202:205], v[112:115]
	v_mfma_f32_16x16x32_bf16 v[108:111], v[210:213], v[198:201], v[108:111]
	v_mfma_f32_16x16x32_bf16 v[104:107], v[210:213], v[194:197], v[104:107]
	v_mfma_f32_16x16x32_bf16 v[84:87], v[210:213], v[190:193], v[84:87]
	v_mfma_f32_16x16x32_bf16 v[72:75], v[210:213], v[186:189], v[72:75]
	v_mfma_f32_16x16x32_bf16 v[60:63], v[210:213], v[182:185], v[60:63]
	v_mfma_f32_16x16x32_bf16 v[48:51], v[210:213], v[178:181], v[48:51]
	v_mfma_f32_16x16x32_bf16 v[36:39], v[210:213], v[146:149], v[36:39]
	v_mfma_f32_16x16x32_bf16 v[100:103], v[206:209], v[202:205], v[100:103]
	v_mfma_f32_16x16x32_bf16 v[96:99], v[206:209], v[198:201], v[96:99]
	v_mfma_f32_16x16x32_bf16 v[92:95], v[206:209], v[194:197], v[92:95]
	v_mfma_f32_16x16x32_bf16 v[88:91], v[206:209], v[190:193], v[88:91]
	v_mfma_f32_16x16x32_bf16 v[76:79], v[206:209], v[186:189], v[76:79]
	v_mfma_f32_16x16x32_bf16 v[64:67], v[206:209], v[182:185], v[64:67]
	v_mfma_f32_16x16x32_bf16 v[52:55], v[206:209], v[178:181], v[52:55]
	v_mfma_f32_16x16x32_bf16 v[40:43], v[206:209], v[146:149], v[40:43]
	s_setprio 0
	s_lshl_b32 s1, s70, 8
	s_add_i32 s0, s0, s1
	s_and_b32 s6, s0, 0x1f80
	s_ashr_i32 s0, s0, 9
	s_lshr_b32 s7, s71, 3
	s_and_b32 s72, s0, -16
	s_cmp_lg_u32 s7, 6
	s_mov_b64 s[14:15], -1
	s_barrier
	s_cbranch_scc0 .LBB0_774
	s_cmp_lt_u32 s71, 8
	s_cselect_b64 s[14:15], -1, 0
	s_mov_b64 s[16:17], 0xc0
	s_and_b64 vcc, exec, s[14:15]
	s_cbranch_vccnz .LBB0_728
	s_cmp_lt_i32 s7, 3
	s_cbranch_scc1 .LBB0_721
	s_cmp_gt_i32 s7, 3
	s_cbranch_scc0 .LBB0_722
	s_cmp_eq_u32 s7, 4
	s_mov_b64 s[52:53], -1
	s_cbranch_scc0 .LBB0_720
	s_mov_b64 s[52:53], 0

.LBB0_907:
	s_and_b32 s17, s16, 1
	s_xor_b32 s18, s17, 1
	s_lshl_b32 s33, s18, 14
	v_lshl_add_u64 v[150:151], v[146:147], 0, s[14:15]
	s_add_i32 s33, s6, s33
	v_lshl_add_u64 v[178:179], v[150:151], 0, 64
	s_mov_b32 m0, s33
	v_lshl_add_u64 v[180:181], v[150:151], 0, s[38:39]
	global_load_lds_dwordx4 v[178:179], off
	s_add_i32 m0, s33, 0x400
	v_lshl_add_u64 v[182:183], v[150:151], 0, s[40:41]
	s_lshl_b32 s18, s18, 13
	global_load_lds_dwordx4 v[180:181], off
	s_add_i32 m0, s33, 0x800
	v_lshl_add_u64 v[172:173], v[148:149], 0, s[14:15]
	v_lshl_add_u64 v[150:151], v[150:151], 0, s[42:43]
	s_add_i32 s18, s7, s18
	global_load_lds_dwordx4 v[182:183], off
	s_add_i32 m0, s33, 0xc00
	v_lshl_add_u64 v[184:185], v[172:173], 0, 64
	global_load_lds_dwordx4 v[150:151], off
	s_add_i32 m0, s18, 0x8000
	v_lshl_add_u64 v[172:173], v[172:173], 0, s[38:39]
	global_load_lds_dwordx4 v[184:185], off
	s_add_i32 m0, s18, 0x8400
	v_lshl_add_u32 v145, s17, 14, v136
	global_load_lds_dwordx4 v[172:173], off
	v_lshl_or_b32 v150, s17, 13, v143
	ds_read_b128 v[178:181], v145
	ds_read_b128 v[182:185], v145 offset:1024
	ds_read_b128 v[186:189], v145 offset:2048
	ds_read_b128 v[190:193], v145 offset:3072
	ds_read_b128 v[194:197], v145 offset:4096
	ds_read_b128 v[198:201], v145 offset:5120
	ds_read_b128 v[202:205], v145 offset:6144
	ds_read_b128 v[206:209], v145 offset:7168
	ds_read_b128 v[210:213], v150 offset:32768
	ds_read_b128 v[214:217], v150 offset:33792
	ds_read_b128 v[218:221], v150 offset:34816
	ds_read_b128 v[222:225], v150 offset:35840
	s_add_i32 s16, s16, 1
	s_setprio 1
	s_waitcnt lgkmcnt(0)
	v_mfma_f32_16x16x32_bf16 v[124:127], v[178:181], v[210:213], v[124:127]
	v_mfma_f32_16x16x32_bf16 v[120:123], v[178:181], v[214:217], v[120:123]
	v_mfma_f32_16x16x32_bf16 v[116:119], v[178:181], v[218:221], v[116:119]
	v_mfma_f32_16x16x32_bf16 v[112:115], v[178:181], v[222:225], v[112:115]
	v_mfma_f32_16x16x32_bf16 v[108:111], v[182:185], v[210:213], v[108:111]
	v_mfma_f32_16x16x32_bf16 v[104:107], v[182:185], v[214:217], v[104:107]
	v_mfma_f32_16x16x32_bf16 v[100:103], v[182:185], v[218:221], v[100:103]
	v_mfma_f32_16x16x32_bf16 v[96:99], v[182:185], v[222:225], v[96:99]
	v_mfma_f32_16x16x32_bf16 v[92:95], v[186:189], v[210:213], v[92:95]
	v_mfma_f32_16x16x32_bf16 v[88:91], v[186:189], v[214:217], v[88:91]
	v_mfma_f32_16x16x32_bf16 v[84:87], v[186:189], v[218:221], v[84:87]
	v_mfma_f32_16x16x32_bf16 v[80:83], v[186:189], v[222:225], v[80:83]
	v_mfma_f32_16x16x32_bf16 v[76:79], v[190:193], v[210:213], v[76:79]
	v_mfma_f32_16x16x32_bf16 v[72:75], v[190:193], v[214:217], v[72:75]
	v_mfma_f32_16x16x32_bf16 v[68:71], v[190:193], v[218:221], v[68:71]
	v_mfma_f32_16x16x32_bf16 v[64:67], v[190:193], v[222:225], v[64:67]
	v_mfma_f32_16x16x32_bf16 v[60:63], v[194:197], v[210:213], v[60:63]
	v_mfma_f32_16x16x32_bf16 v[56:59], v[194:197], v[214:217], v[56:59]
	v_mfma_f32_16x16x32_bf16 v[52:55], v[194:197], v[218:221], v[52:55]
	v_mfma_f32_16x16x32_bf16 v[48:51], v[194:197], v[222:225], v[48:51]
	v_mfma_f32_16x16x32_bf16 v[44:47], v[198:201], v[210:213], v[44:47]
	v_mfma_f32_16x16x32_bf16 v[40:43], v[198:201], v[214:217], v[40:43]
	v_mfma_f32_16x16x32_bf16 v[36:39], v[198:201], v[218:221], v[36:39]
	v_mfma_f32_16x16x32_bf16 v[32:35], v[198:201], v[222:225], v[32:35]
	v_mfma_f32_16x16x32_bf16 v[28:31], v[202:205], v[210:213], v[28:31]
	v_mfma_f32_16x16x32_bf16 v[24:27], v[202:205], v[214:217], v[24:27]
	v_mfma_f32_16x16x32_bf16 v[20:23], v[202:205], v[218:221], v[20:23]
	v_mfma_f32_16x16x32_bf16 v[16:19], v[202:205], v[222:225], v[16:19]
	v_mfma_f32_16x16x32_bf16 v[12:15], v[206:209], v[210:213], v[12:15]
	v_mfma_f32_16x16x32_bf16 v[8:11], v[206:209], v[214:217], v[8:11]
	v_mfma_f32_16x16x32_bf16 v[4:7], v[206:209], v[218:221], v[4:7]
	v_mfma_f32_16x16x32_bf16 v[0:3], v[206:209], v[222:225], v[0:3]
	s_setprio 0
	s_add_u32 s14, s14, 64
	s_addc_u32 s15, s15, 0
	s_cmpk_lg_i32 s14, 0xfc0
	s_waitcnt vmcnt(0)
	s_barrier
	s_cbranch_scc1 .LBB0_907
	ds_read_b128 v[146:149], v143 offset:44032
	ds_read_b128 v[178:181], v143 offset:43008
	ds_read_b128 v[182:185], v143 offset:41984
	ds_read_b128 v[186:189], v143 offset:40960
	ds_read_b128 v[190:193], v136 offset:23552
	ds_read_b128 v[194:197], v136 offset:22528
	ds_read_b128 v[198:201], v136 offset:21504
	ds_read_b128 v[202:205], v136 offset:20480
	ds_read_b128 v[206:209], v136 offset:19456
	ds_read_b128 v[210:213], v136 offset:18432
	ds_read_b128 v[214:217], v136 offset:17408
	ds_read_b128 v[218:221], v136 offset:16384
	s_setprio 1
	s_waitcnt lgkmcnt(0)
	v_mfma_f32_16x16x32_bf16 v[124:127], v[218:221], v[186:189], v[124:127]
	v_mfma_f32_16x16x32_bf16 v[120:123], v[218:221], v[182:185], v[120:123]
	v_mfma_f32_16x16x32_bf16 v[116:119], v[218:221], v[178:181], v[116:119]
	v_mfma_f32_16x16x32_bf16 v[112:115], v[218:221], v[146:149], v[112:115]
	v_mfma_f32_16x16x32_bf16 v[108:111], v[214:217], v[186:189], v[108:111]
	v_mfma_f32_16x16x32_bf16 v[104:107], v[214:217], v[182:185], v[104:107]
	v_mfma_f32_16x16x32_bf16 v[100:103], v[214:217], v[178:181], v[100:103]
	v_mfma_f32_16x16x32_bf16 v[96:99], v[214:217], v[146:149], v[96:99]
	v_mfma_f32_16x16x32_bf16 v[92:95], v[210:213], v[186:189], v[92:95]
	v_mfma_f32_16x16x32_bf16 v[88:91], v[210:213], v[182:185], v[88:91]
	v_mfma_f32_16x16x32_bf16 v[84:87], v[210:213], v[178:181], v[84:87]
	v_mfma_f32_16x16x32_bf16 v[80:83], v[210:213], v[146:149], v[80:83]
	v_mfma_f32_16x16x32_bf16 v[76:79], v[206:209], v[186:189], v[76:79]
	v_mfma_f32_16x16x32_bf16 v[72:75], v[206:209], v[182:185], v[72:75]
	v_mfma_f32_16x16x32_bf16 v[210:213], v[206:209], v[178:181], v[68:71]
	v_mfma_f32_16x16x32_bf16 v[206:209], v[206:209], v[146:149], v[64:67]
	v_mfma_f32_16x16x32_bf16 v[60:63], v[202:205], v[186:189], v[60:63]
	v_mfma_f32_16x16x32_bf16 v[56:59], v[202:205], v[182:185], v[56:59]
	v_mfma_f32_16x16x32_bf16 v[52:55], v[202:205], v[178:181], v[52:55]
	v_mfma_f32_16x16x32_bf16 v[48:51], v[202:205], v[146:149], v[48:51]
	v_mfma_f32_16x16x32_bf16 v[44:47], v[198:201], v[186:189], v[44:47]
	v_mfma_f32_16x16x32_bf16 v[40:43], v[198:201], v[182:185], v[40:43]
	v_mfma_f32_16x16x32_bf16 v[36:39], v[198:201], v[178:181], v[36:39]
	v_mfma_f32_16x16x32_bf16 v[32:35], v[198:201], v[146:149], v[32:35]
	v_mfma_f32_16x16x32_bf16 v[28:31], v[194:197], v[186:189], v[28:31]
	v_mfma_f32_16x16x32_bf16 v[24:27], v[194:197], v[182:185], v[24:27]
	v_mfma_f32_16x16x32_bf16 v[20:23], v[194:197], v[178:181], v[20:23]
	v_mfma_f32_16x16x32_bf16 v[16:19], v[194:197], v[146:149], v[16:19]
	v_mfma_f32_16x16x32_bf16 v[12:15], v[190:193], v[186:189], v[12:15]
	v_mfma_f32_16x16x32_bf16 v[8:11], v[190:193], v[182:185], v[8:11]
	v_mfma_f32_16x16x32_bf16 v[4:7], v[190:193], v[178:181], v[4:7]
	v_mfma_f32_16x16x32_bf16 v[0:3], v[190:193], v[146:149], v[0:3]
	s_setprio 0
	v_and_b32_e32 v65, 64, v167
	v_xor_b32_e32 v64, 16, v167
	v_add_u32_e32 v65, 64, v65
	v_cmp_lt_i32_e32 vcc, v64, v65
	v_cvt_pk_bf16_f32 v65, v126, v127
	v_cvt_pk_bf16_f32 v67, v110, v111
	v_cndmask_b32_e32 v64, v167, v64, vcc
	s_lshl_b32 s7, s70, 8
	v_lshlrev_b32_e32 v136, 2, v64
	v_cvt_pk_bf16_f32 v64, v124, v125
	v_cvt_pk_bf16_f32 v66, v108, v109
	v_cndmask_b32_e64 v68, v65, v67, s[10:11]
	s_add_i32 s1, s1, s7
	v_cndmask_b32_e64 v69, v64, v66, s[10:11]
	ds_bpermute_b32 v70, v136, v68
	s_lshl_b32 s6, s71, 1
	s_and_b32 s7, s1, 0x1f80
	s_ashr_i32 s1, s1, 9
	ds_bpermute_b32 v71, v136, v69
	s_and_b32 s6, s6, 14
	s_and_b32 s1, s1, 0x3fffff0
	s_or_b32 s1, s6, s1
	s_or_b32 s0, s1, s0
	v_cndmask_b32_e64 v65, v67, v65, s[10:11]
	v_lshl_or_b32 v108, s0, 6, v129
	v_cndmask_b32_e64 v64, v66, v64, s[10:11]
	s_waitcnt lgkmcnt(1)
	v_cndmask_b32_e64 v69, v65, v70, s[10:11]
	v_cndmask_b32_e64 v67, v70, v65, s[10:11]
	v_cvt_pk_bf16_f32 v70, v120, v121
	v_cvt_pk_bf16_f32 v104, v104, v105
	s_waitcnt lgkmcnt(0)
	v_cndmask_b32_e64 v68, v64, v71, s[10:11]
	v_cndmask_b32_e64 v66, v71, v64, s[10:11]
	v_ashrrev_i32_e32 v109, 31, v108
	v_cvt_pk_bf16_f32 v71, v122, v123
	v_cvt_pk_bf16_f32 v105, v106, v107
	v_cndmask_b32_e64 v107, v70, v104, s[10:11]
	v_lshlrev_b64 v[64:65], 14, v[108:109]
	v_cndmask_b32_e64 v106, v71, v105, s[10:11]
	ds_bpermute_b32 v107, v136, v107
	v_lshl_add_u64 v[64:65], s[28:29], 0, v[64:65]
	s_lshl_b32 s18, s7, 1
	ds_bpermute_b32 v106, v136, v106
	v_lshl_add_u64 v[64:65], v[64:65], 0, s[18:19]
	v_mov_b32_e32 v143, v137
	v_lshl_add_u64 v[64:65], v[64:65], 0, v[142:143]
	s_waitcnt lgkmcnt(0)
	s_barrier
	global_store_dwordx4 v[64:65], v[66:69], off
	v_cvt_pk_bf16_f32 v92, v92, v93
	v_cvt_pk_bf16_f32 v93, v94, v95
	v_cndmask_b32_e64 v66, v104, v70, s[10:11]
	v_cndmask_b32_e64 v67, v105, v71, s[10:11]
	v_cndmask_b32_e64 v70, v66, v107, s[10:11]
	v_cndmask_b32_e64 v68, v107, v66, s[10:11]
	v_or_b32_e32 v66, 16, v108
	v_cndmask_b32_e64 v71, v67, v106, s[10:11]
	v_cndmask_b32_e64 v69, v106, v67, s[10:11]
	v_ashrrev_i32_e32 v67, 31, v66
	v_cvt_pk_bf16_f32 v76, v76, v77
	v_cvt_pk_bf16_f32 v77, v78, v79
	v_lshlrev_b64 v[66:67], 14, v[66:67]
	v_cndmask_b32_e64 v78, v93, v77, s[10:11]
	v_cndmask_b32_e64 v79, v92, v76, s[10:11]
	v_lshl_add_u64 v[66:67], s[28:29], 0, v[66:67]
	ds_bpermute_b32 v94, v136, v78
	ds_bpermute_b32 v95, v136, v79
	v_cvt_pk_bf16_f32 v88, v88, v89
	v_cvt_pk_bf16_f32 v89, v90, v91
	v_cvt_pk_bf16_f32 v72, v72, v73
	v_cvt_pk_bf16_f32 v73, v74, v75
	v_cvt_pk_bf16_f32 v60, v60, v61
	v_cvt_pk_bf16_f32 v61, v62, v63
	v_cvt_pk_bf16_f32 v44, v44, v45
	v_cvt_pk_bf16_f32 v45, v46, v47
	v_cvt_pk_bf16_f32 v56, v56, v57
	v_cvt_pk_bf16_f32 v57, v58, v59
	v_cvt_pk_bf16_f32 v40, v40, v41
	v_cvt_pk_bf16_f32 v41, v42, v43
	v_cvt_pk_bf16_f32 v28, v28, v29
	v_cvt_pk_bf16_f32 v29, v30, v31
	v_cvt_pk_bf16_f32 v12, v12, v13
	v_cvt_pk_bf16_f32 v13, v14, v15
	v_cvt_pk_bf16_f32 v24, v24, v25
	v_cvt_pk_bf16_f32 v25, v26, v27
	v_cvt_pk_bf16_f32 v8, v8, v9
	v_cvt_pk_bf16_f32 v9, v10, v11
	v_lshl_add_u64 v[66:67], v[66:67], 0, s[18:19]
	v_cvt_pk_bf16_f32 v104, v116, v117
	v_cvt_pk_bf16_f32 v100, v100, v101
	v_cndmask_b32_e64 v74, v89, v73, s[10:11]
	v_cndmask_b32_e64 v75, v88, v72, s[10:11]
	v_cndmask_b32_e64 v46, v61, v45, s[10:11]
	v_cndmask_b32_e64 v47, v60, v44, s[10:11]
	v_cndmask_b32_e64 v42, v57, v41, s[10:11]
	v_cndmask_b32_e64 v43, v56, v40, s[10:11]
	v_cndmask_b32_e64 v14, v29, v13, s[10:11]
	v_cndmask_b32_e64 v15, v28, v12, s[10:11]
	v_cndmask_b32_e64 v10, v25, v9, s[10:11]
	v_cndmask_b32_e64 v11, v24, v8, s[10:11]
	v_lshl_add_u64 v[66:67], v[66:67], 0, v[142:143]
	v_cvt_pk_bf16_f32 v105, v118, v119
	v_cvt_pk_bf16_f32 v101, v102, v103
	v_cndmask_b32_e64 v103, v104, v100, s[10:11]
	ds_bpermute_b32 v90, v136, v74
	ds_bpermute_b32 v91, v136, v75
	ds_bpermute_b32 v62, v136, v46
	ds_bpermute_b32 v63, v136, v47
	ds_bpermute_b32 v58, v136, v42
	ds_bpermute_b32 v59, v136, v43
	ds_bpermute_b32 v30, v136, v14
	ds_bpermute_b32 v31, v136, v15
	ds_bpermute_b32 v26, v136, v10
	ds_bpermute_b32 v27, v136, v11
	v_cndmask_b32_e64 v102, v105, v101, s[10:11]
	ds_bpermute_b32 v107, v136, v103
	global_store_dwordx4 v[66:67], v[68:71], off
	v_cvt_pk_bf16_f32 v96, v96, v97
	ds_bpermute_b32 v106, v136, v102
	v_cvt_pk_bf16_f32 v70, v112, v113
	v_cvt_pk_bf16_f32 v71, v114, v115
	v_cvt_pk_bf16_f32 v97, v98, v99
	v_cndmask_b32_e64 v99, v70, v96, s[10:11]
	v_cndmask_b32_e64 v76, v76, v92, s[10:11]
	v_cndmask_b32_e64 v77, v77, v93, s[10:11]
	v_cndmask_b32_e64 v69, v101, v105, s[10:11]
	v_cndmask_b32_e64 v98, v71, v97, s[10:11]
	ds_bpermute_b32 v105, v136, v99
	s_waitcnt lgkmcnt(14)
	v_cndmask_b32_e64 v79, v77, v94, s[10:11]
	s_waitcnt lgkmcnt(13)
	v_cndmask_b32_e64 v78, v76, v95, s[10:11]
	v_cndmask_b32_e64 v77, v94, v77, s[10:11]
	v_cndmask_b32_e64 v76, v95, v76, s[10:11]
	v_cndmask_b32_e64 v68, v100, v104, s[10:11]
	ds_bpermute_b32 v104, v136, v98
	global_store_dwordx4 v[64:65], v[76:79], off offset:64
	v_cndmask_b32_e64 v72, v72, v88, s[10:11]
	v_cndmask_b32_e64 v73, v73, v89, s[10:11]
	v_cvt_pk_bf16_f32 v76, v84, v85
	v_cvt_pk_bf16_f32 v77, v86, v87
	v_cvt_pk_bf16_f32 v78, v210, v211
	v_cvt_pk_bf16_f32 v79, v212, v213
	v_cndmask_b32_e64 v44, v44, v60, s[10:11]
	v_cndmask_b32_e64 v45, v45, v61, s[10:11]
	v_cndmask_b32_e64 v40, v40, v56, s[10:11]
	v_cndmask_b32_e64 v41, v41, v57, s[10:11]
	v_cndmask_b32_e64 v12, v12, v28, s[10:11]
	v_cndmask_b32_e64 v13, v13, v29, s[10:11]
	v_cndmask_b32_e64 v8, v8, v24, s[10:11]
	v_cndmask_b32_e64 v9, v9, v25, s[10:11]
	s_waitcnt lgkmcnt(13)
	v_cndmask_b32_e64 v75, v73, v90, s[10:11]
	s_waitcnt lgkmcnt(12)
	v_cndmask_b32_e64 v74, v72, v91, s[10:11]
	v_cndmask_b32_e64 v73, v90, v73, s[10:11]
	v_cndmask_b32_e64 v72, v91, v72, s[10:11]
	v_cndmask_b32_e64 v84, v77, v79, s[10:11]
	v_cndmask_b32_e64 v85, v76, v78, s[10:11]
	s_waitcnt lgkmcnt(11)
	v_cndmask_b32_e64 v47, v45, v62, s[10:11]
	s_waitcnt lgkmcnt(10)
	v_cndmask_b32_e64 v46, v44, v63, s[10:11]
	v_cndmask_b32_e64 v45, v62, v45, s[10:11]
	v_cndmask_b32_e64 v44, v63, v44, s[10:11]
	s_waitcnt lgkmcnt(9)
	v_cndmask_b32_e64 v43, v41, v58, s[10:11]
	s_waitcnt lgkmcnt(8)
	v_cndmask_b32_e64 v42, v40, v59, s[10:11]
	v_cndmask_b32_e64 v41, v58, v41, s[10:11]
	v_cndmask_b32_e64 v40, v59, v40, s[10:11]
	s_waitcnt lgkmcnt(7)
	v_cndmask_b32_e64 v15, v13, v30, s[10:11]
	s_waitcnt lgkmcnt(6)
	v_cndmask_b32_e64 v14, v12, v31, s[10:11]
	v_cndmask_b32_e64 v13, v30, v13, s[10:11]
	v_cndmask_b32_e64 v12, v31, v12, s[10:11]
	s_waitcnt lgkmcnt(5)
	v_cndmask_b32_e64 v11, v9, v26, s[10:11]
	s_waitcnt lgkmcnt(4)
	v_cndmask_b32_e64 v10, v8, v27, s[10:11]
	v_cndmask_b32_e64 v9, v26, v9, s[10:11]
	v_cndmask_b32_e64 v8, v27, v8, s[10:11]
	s_waitcnt lgkmcnt(3)
	v_cndmask_b32_e64 v102, v68, v107, s[10:11]
	v_cndmask_b32_e64 v100, v107, v68, s[10:11]
	v_or_b32_e32 v68, 32, v108
	ds_bpermute_b32 v84, v136, v84
	ds_bpermute_b32 v85, v136, v85
	global_store_dwordx4 v[66:67], v[72:75], off offset:64
	global_store_dwordx4 v[64:65], v[44:47], off offset:128
	v_cvt_pk_bf16_f32 v36, v36, v37
	v_cndmask_b32_e64 v72, v78, v76, s[10:11]
	v_cndmask_b32_e64 v73, v79, v77, s[10:11]
	v_cvt_pk_bf16_f32 v76, v80, v81
	v_cvt_pk_bf16_f32 v77, v82, v83
	v_cvt_pk_bf16_f32 v78, v206, v207
	v_cvt_pk_bf16_f32 v79, v208, v209
	v_cvt_pk_bf16_f32 v44, v52, v53
	v_cvt_pk_bf16_f32 v45, v54, v55
	v_cvt_pk_bf16_f32 v37, v38, v39
	global_store_dwordx4 v[66:67], v[40:43], off offset:128
	v_cvt_pk_bf16_f32 v32, v32, v33
	v_cvt_pk_bf16_f32 v33, v34, v35
	v_cvt_pk_bf16_f32 v40, v48, v49
	v_cvt_pk_bf16_f32 v41, v50, v51
	global_store_dwordx4 v[64:65], v[12:15], off offset:192
	v_cvt_pk_bf16_f32 v4, v4, v5
	v_cvt_pk_bf16_f32 v5, v6, v7
	v_cvt_pk_bf16_f32 v12, v20, v21
	v_cvt_pk_bf16_f32 v13, v22, v23
	global_store_dwordx4 v[66:67], v[8:11], off offset:192
	v_cvt_pk_bf16_f32 v0, v0, v1
	v_cvt_pk_bf16_f32 v1, v2, v3
	v_cvt_pk_bf16_f32 v8, v16, v17
	v_cvt_pk_bf16_f32 v9, v18, v19
	s_waitcnt lgkmcnt(4)
	v_cndmask_b32_e64 v103, v69, v106, s[10:11]
	v_cndmask_b32_e64 v101, v106, v69, s[10:11]
	v_ashrrev_i32_e32 v69, 31, v68
	v_cndmask_b32_e64 v70, v96, v70, s[10:11]
	v_cndmask_b32_e64 v80, v77, v79, s[10:11]
	v_cndmask_b32_e64 v81, v76, v78, s[10:11]
	v_cndmask_b32_e64 v38, v45, v37, s[10:11]
	v_cndmask_b32_e64 v39, v44, v36, s[10:11]
	v_cndmask_b32_e64 v34, v41, v33, s[10:11]
	v_cndmask_b32_e64 v35, v40, v32, s[10:11]
	v_cndmask_b32_e64 v6, v13, v5, s[10:11]
	v_cndmask_b32_e64 v7, v12, v4, s[10:11]
	v_cndmask_b32_e64 v2, v9, v1, s[10:11]
	v_cndmask_b32_e64 v3, v8, v0, s[10:11]
	v_lshlrev_b64 v[68:69], 14, v[68:69]
	v_cndmask_b32_e64 v71, v97, v71, s[10:11]
	s_waitcnt lgkmcnt(3)
	v_cndmask_b32_e64 v98, v70, v105, s[10:11]
	v_cndmask_b32_e64 v96, v105, v70, s[10:11]
	v_or_b32_e32 v70, 48, v108
	ds_bpermute_b32 v80, v136, v80
	ds_bpermute_b32 v81, v136, v81
	ds_bpermute_b32 v46, v136, v38
	ds_bpermute_b32 v47, v136, v39
	ds_bpermute_b32 v42, v136, v34
	ds_bpermute_b32 v43, v136, v35
	ds_bpermute_b32 v14, v136, v6
	ds_bpermute_b32 v15, v136, v7
	ds_bpermute_b32 v10, v136, v2
	ds_bpermute_b32 v11, v136, v3
	v_lshl_add_u64 v[68:69], s[28:29], 0, v[68:69]
	s_waitcnt lgkmcnt(12)
	v_cndmask_b32_e64 v99, v71, v104, s[10:11]
	v_cndmask_b32_e64 v97, v104, v71, s[10:11]
	v_ashrrev_i32_e32 v71, 31, v70
	v_lshl_add_u64 v[68:69], v[68:69], 0, s[18:19]
	v_lshlrev_b64 v[70:71], 14, v[70:71]
	v_lshl_add_u64 v[68:69], v[68:69], 0, v[142:143]
	v_lshl_add_u64 v[70:71], s[28:29], 0, v[70:71]
	s_waitcnt lgkmcnt(11)
	v_cndmask_b32_e64 v75, v73, v84, s[10:11]
	s_waitcnt lgkmcnt(10)
	v_cndmask_b32_e64 v74, v72, v85, s[10:11]
	v_cndmask_b32_e64 v73, v84, v73, s[10:11]
	v_cndmask_b32_e64 v72, v85, v72, s[10:11]
	v_lshl_add_u64 v[70:71], v[70:71], 0, s[18:19]
	global_store_dwordx4 v[68:69], v[72:75], off offset:64
	v_cndmask_b32_e64 v36, v36, v44, s[10:11]
	v_cndmask_b32_e64 v37, v37, v45, s[10:11]
	v_cndmask_b32_e64 v72, v78, v76, s[10:11]
	v_cndmask_b32_e64 v73, v79, v77, s[10:11]
	v_cndmask_b32_e64 v32, v32, v40, s[10:11]
	v_cndmask_b32_e64 v33, v33, v41, s[10:11]
	v_cndmask_b32_e64 v4, v4, v12, s[10:11]
	v_cndmask_b32_e64 v5, v5, v13, s[10:11]
	v_cndmask_b32_e64 v0, v0, v8, s[10:11]
	v_cndmask_b32_e64 v1, v1, v9, s[10:11]
	v_lshl_add_u64 v[70:71], v[70:71], 0, v[142:143]
	s_waitcnt lgkmcnt(9)
	v_cndmask_b32_e64 v75, v73, v80, s[10:11]
	s_waitcnt lgkmcnt(8)
	v_cndmask_b32_e64 v74, v72, v81, s[10:11]
	v_cndmask_b32_e64 v73, v80, v73, s[10:11]
	v_cndmask_b32_e64 v72, v81, v72, s[10:11]
	s_waitcnt lgkmcnt(7)
	v_cndmask_b32_e64 v39, v37, v46, s[10:11]
	s_waitcnt lgkmcnt(6)
	v_cndmask_b32_e64 v38, v36, v47, s[10:11]
	v_cndmask_b32_e64 v37, v46, v37, s[10:11]
	v_cndmask_b32_e64 v36, v47, v36, s[10:11]
	s_waitcnt lgkmcnt(5)
	v_cndmask_b32_e64 v35, v33, v42, s[10:11]
	s_waitcnt lgkmcnt(4)
	v_cndmask_b32_e64 v34, v32, v43, s[10:11]
	v_cndmask_b32_e64 v33, v42, v33, s[10:11]
	v_cndmask_b32_e64 v32, v43, v32, s[10:11]
	s_waitcnt lgkmcnt(3)
	v_cndmask_b32_e64 v7, v5, v14, s[10:11]
	s_waitcnt lgkmcnt(2)
	v_cndmask_b32_e64 v6, v4, v15, s[10:11]
	v_cndmask_b32_e64 v5, v14, v5, s[10:11]
	v_cndmask_b32_e64 v4, v15, v4, s[10:11]
	s_waitcnt lgkmcnt(1)
	v_cndmask_b32_e64 v3, v1, v10, s[10:11]
	s_waitcnt lgkmcnt(0)
	v_cndmask_b32_e64 v2, v0, v11, s[10:11]
	v_cndmask_b32_e64 v1, v10, v1, s[10:11]
	v_cndmask_b32_e64 v0, v11, v0, s[10:11]
	global_store_dwordx4 v[68:69], v[100:103], off
	global_store_dwordx4 v[70:71], v[96:99], off
	global_store_dwordx4 v[70:71], v[72:75], off offset:64
	global_store_dwordx4 v[68:69], v[36:39], off offset:128
	global_store_dwordx4 v[70:71], v[32:35], off offset:128
	global_store_dwordx4 v[68:69], v[4:7], off offset:192
	global_store_dwordx4 v[70:71], v[0:3], off offset:192
	s_branch .LBB0_705

.LBB0_1177:
	s_and_b32 s49, s48, 1
	s_xor_b32 s50, s49, 1
	s_lshl_b32 s51, s50, 14
	v_lshl_add_u64 v[150:151], v[136:137], 0, s[44:45]
	s_add_i32 s51, s33, s51
	v_lshl_add_u64 v[160:161], v[150:151], 0, 64
	s_mov_b32 m0, s51
	v_lshl_add_u64 v[162:163], v[150:151], 0, s[38:39]
	global_load_lds_dwordx4 v[160:161], off
	s_add_i32 m0, s51, 0x400
	v_lshl_add_u64 v[164:165], v[150:151], 0, s[40:41]
	s_lshl_b32 s50, s50, 13
	global_load_lds_dwordx4 v[162:163], off
	s_add_i32 m0, s51, 0x800
	v_lshl_add_u64 v[152:153], v[138:139], 0, s[44:45]
	v_lshl_add_u64 v[150:151], v[150:151], 0, s[42:43]
	s_add_i32 s50, s47, s50
	global_load_lds_dwordx4 v[164:165], off
	s_add_i32 m0, s51, 0xc00
	v_lshl_add_u64 v[166:167], v[152:153], 0, 64
	global_load_lds_dwordx4 v[150:151], off
	s_add_i32 m0, s50, 0x8000
	v_lshl_add_u64 v[152:153], v[152:153], 0, s[38:39]
	global_load_lds_dwordx4 v[166:167], off
	s_add_i32 m0, s50, 0x8400
	v_lshl_or_b32 v149, s49, 13, v147
	global_load_lds_dwordx4 v[152:153], off
	v_lshl_add_u32 v172, s49, 14, v148
	ds_read_b128 v[150:153], v149 offset:32768
	ds_read_b128 v[160:163], v149 offset:33792
	ds_read_b128 v[164:167], v149 offset:34816
	ds_read_b128 v[168:171], v149 offset:35840
	ds_read_b128 v[178:181], v172
	ds_read_b128 v[182:185], v172 offset:1024
	ds_read_b128 v[186:189], v172 offset:2048
	ds_read_b128 v[190:193], v172 offset:3072
	ds_read_b128 v[194:197], v172 offset:4096
	ds_read_b128 v[198:201], v172 offset:5120
	ds_read_b128 v[202:205], v172 offset:6144
	ds_read_b128 v[206:209], v172 offset:7168
	s_add_i32 s48, s48, 1
	s_setprio 1
	s_waitcnt lgkmcnt(0)
	v_mfma_f32_16x16x32_bf16 v[124:127], v[150:153], v[178:181], v[124:127]
	v_mfma_f32_16x16x32_bf16 v[120:123], v[150:153], v[182:185], v[120:123]
	v_mfma_f32_16x16x32_bf16 v[116:119], v[150:153], v[186:189], v[116:119]
	v_mfma_f32_16x16x32_bf16 v[112:115], v[150:153], v[190:193], v[112:115]
	v_mfma_f32_16x16x32_bf16 v[60:63], v[150:153], v[194:197], v[60:63]
	v_mfma_f32_16x16x32_bf16 v[44:47], v[150:153], v[198:201], v[44:47]
	v_mfma_f32_16x16x32_bf16 v[28:31], v[150:153], v[202:205], v[28:31]
	v_mfma_f32_16x16x32_bf16 v[12:15], v[150:153], v[206:209], v[12:15]
	v_mfma_f32_16x16x32_bf16 v[108:111], v[160:163], v[178:181], v[108:111]
	v_mfma_f32_16x16x32_bf16 v[104:107], v[160:163], v[182:185], v[104:107]
	v_mfma_f32_16x16x32_bf16 v[100:103], v[160:163], v[186:189], v[100:103]
	v_mfma_f32_16x16x32_bf16 v[96:99], v[160:163], v[190:193], v[96:99]
	v_mfma_f32_16x16x32_bf16 v[56:59], v[160:163], v[194:197], v[56:59]
	v_mfma_f32_16x16x32_bf16 v[40:43], v[160:163], v[198:201], v[40:43]
	v_mfma_f32_16x16x32_bf16 v[24:27], v[160:163], v[202:205], v[24:27]
	v_mfma_f32_16x16x32_bf16 v[8:11], v[160:163], v[206:209], v[8:11]
	v_mfma_f32_16x16x32_bf16 v[92:95], v[164:167], v[178:181], v[92:95]
	v_mfma_f32_16x16x32_bf16 v[88:91], v[164:167], v[182:185], v[88:91]
	v_mfma_f32_16x16x32_bf16 v[84:87], v[164:167], v[186:189], v[84:87]
	v_mfma_f32_16x16x32_bf16 v[80:83], v[164:167], v[190:193], v[80:83]
	v_mfma_f32_16x16x32_bf16 v[52:55], v[164:167], v[194:197], v[52:55]
	v_mfma_f32_16x16x32_bf16 v[36:39], v[164:167], v[198:201], v[36:39]
	v_mfma_f32_16x16x32_bf16 v[20:23], v[164:167], v[202:205], v[20:23]
	v_mfma_f32_16x16x32_bf16 v[4:7], v[164:167], v[206:209], v[4:7]
	v_mfma_f32_16x16x32_bf16 v[76:79], v[168:171], v[178:181], v[76:79]
	v_mfma_f32_16x16x32_bf16 v[72:75], v[168:171], v[182:185], v[72:75]
	v_mfma_f32_16x16x32_bf16 v[68:71], v[168:171], v[186:189], v[68:71]
	v_mfma_f32_16x16x32_bf16 v[64:67], v[168:171], v[190:193], v[64:67]
	v_mfma_f32_16x16x32_bf16 v[48:51], v[168:171], v[194:197], v[48:51]
	v_mfma_f32_16x16x32_bf16 v[32:35], v[168:171], v[198:201], v[32:35]
	v_mfma_f32_16x16x32_bf16 v[16:19], v[168:171], v[202:205], v[16:19]
	v_mfma_f32_16x16x32_bf16 v[0:3], v[168:171], v[206:209], v[0:3]
	s_setprio 0
	s_add_u32 s44, s44, 64
	s_addc_u32 s45, s45, 0
	s_cmpk_eq_i32 s44, 0xfc0
	s_waitcnt vmcnt(0)
	s_barrier
	s_cbranch_scc0 .LBB0_1177
	ds_read_b128 v[136:139], v148 offset:23552
	ds_read_b128 v[150:153], v148 offset:22528
	ds_read_b128 v[160:163], v148 offset:21504
	ds_read_b128 v[164:167], v148 offset:20480
	ds_read_b128 v[168:171], v148 offset:19456
	ds_read_b128 v[178:181], v148 offset:18432
	ds_read_b128 v[182:185], v148 offset:17408
	ds_read_b128 v[186:189], v148 offset:16384
	ds_read_b128 v[190:193], v147 offset:44032
	ds_read_b128 v[194:197], v147 offset:43008
	ds_read_b128 v[198:201], v147 offset:41984
	ds_read_b128 v[202:205], v147 offset:40960
	s_setprio 1
	s_waitcnt lgkmcnt(0)
	v_mfma_f32_16x16x32_bf16 v[120:123], v[202:205], v[182:185], v[120:123]
	v_mfma_f32_16x16x32_bf16 v[116:119], v[202:205], v[178:181], v[116:119]
	v_mfma_f32_16x16x32_bf16 v[112:115], v[202:205], v[168:171], v[112:115]
	v_mfma_f32_16x16x32_bf16 v[60:63], v[202:205], v[164:167], v[60:63]
	v_mfma_f32_16x16x32_bf16 v[44:47], v[202:205], v[160:163], v[44:47]
	v_mfma_f32_16x16x32_bf16 v[28:31], v[202:205], v[150:153], v[28:31]
	v_mfma_f32_16x16x32_bf16 v[12:15], v[202:205], v[136:139], v[12:15]
	v_mfma_f32_16x16x32_bf16 v[104:107], v[198:201], v[182:185], v[104:107]
	v_mfma_f32_16x16x32_bf16 v[100:103], v[198:201], v[178:181], v[100:103]
	v_mfma_f32_16x16x32_bf16 v[96:99], v[198:201], v[168:171], v[96:99]
	v_mfma_f32_16x16x32_bf16 v[56:59], v[198:201], v[164:167], v[56:59]
	v_mfma_f32_16x16x32_bf16 v[40:43], v[198:201], v[160:163], v[40:43]
	v_mfma_f32_16x16x32_bf16 v[24:27], v[198:201], v[150:153], v[24:27]
	v_mfma_f32_16x16x32_bf16 v[8:11], v[198:201], v[136:139], v[8:11]
	v_mfma_f32_16x16x32_bf16 v[88:91], v[194:197], v[182:185], v[88:91]
	v_mfma_f32_16x16x32_bf16 v[84:87], v[194:197], v[178:181], v[84:87]
	v_mfma_f32_16x16x32_bf16 v[80:83], v[194:197], v[168:171], v[80:83]
	v_mfma_f32_16x16x32_bf16 v[52:55], v[194:197], v[164:167], v[52:55]
	v_mfma_f32_16x16x32_bf16 v[36:39], v[194:197], v[160:163], v[36:39]
	v_mfma_f32_16x16x32_bf16 v[20:23], v[194:197], v[150:153], v[20:23]
	v_mfma_f32_16x16x32_bf16 v[4:7], v[194:197], v[136:139], v[4:7]
	v_mfma_f32_16x16x32_bf16 v[72:75], v[190:193], v[182:185], v[72:75]
	v_mfma_f32_16x16x32_bf16 v[68:71], v[190:193], v[178:181], v[68:71]
	v_mfma_f32_16x16x32_bf16 v[64:67], v[190:193], v[168:171], v[64:67]
	v_mfma_f32_16x16x32_bf16 v[48:51], v[190:193], v[164:167], v[48:51]
	v_mfma_f32_16x16x32_bf16 v[32:35], v[190:193], v[160:163], v[32:35]
	v_mfma_f32_16x16x32_bf16 v[16:19], v[190:193], v[150:153], v[16:19]
	v_mfma_f32_16x16x32_bf16 v[0:3], v[190:193], v[136:139], v[0:3]
	v_mfma_f32_16x16x32_bf16 v[124:127], v[202:205], v[186:189], v[124:127]
	v_mfma_f32_16x16x32_bf16 v[108:111], v[198:201], v[186:189], v[108:111]
	v_mfma_f32_16x16x32_bf16 v[198:201], v[194:197], v[186:189], v[92:95]
	v_mfma_f32_16x16x32_bf16 v[186:189], v[190:193], v[186:189], v[76:79]
	s_setprio 0
	s_lshl_b32 s0, s0, 8
	s_add_i32 s1, s1, s0
	s_lshl_b32 s33, s22, 7
	s_lshl_b32 s44, s46, 6
	v_or_b32_e32 v76, s1, v129
	s_or_b32 s33, s44, s33
	v_ashrrev_i32_e32 v77, 31, v76
	v_or_b32_e32 v92, s33, v159
	v_lshlrev_b64 v[78:79], 13, v[76:77]
	v_lshl_or_b32 v78, v92, 2, v78
	v_lshl_add_u64 v[94:95], s[10:11], 0, v[78:79]
	s_barrier
	global_load_dwordx4 v[136:139], v[94:95], off
	v_lshl_add_u64 v[78:79], s[12:13], 0, v[78:79]
	s_lshl_b32 s47, s22, 1
	s_lshl_b32 s22, s33, 1
	s_waitcnt vmcnt(0)
	v_pk_add_f32 v[126:127], v[126:127], v[138:139]
	v_pk_add_f32 v[124:125], v[124:125], v[136:137]
	global_store_dwordx4 v[78:79], v[124:127], off
	global_load_dwordx4 v[136:139], v[94:95], off offset:64
	v_cvt_pk_bf16_f32 v93, v124, v125
	v_mul_f32_e32 v125, v125, v125
	v_fmac_f32_e32 v125, v124, v124
	v_cvt_pk_bf16_f32 v147, v126, v127
	v_fmac_f32_e32 v125, v126, v126
	v_fmac_f32_e32 v125, v127, v127
	s_waitcnt vmcnt(0)
	v_pk_add_f32 v[110:111], v[110:111], v[138:139]
	v_pk_add_f32 v[108:109], v[108:109], v[136:137]
	global_store_dwordx4 v[78:79], v[108:111], off offset:64
	global_load_dwordx4 v[136:139], v[94:95], off offset:128
	v_cvt_pk_bf16_f32 v124, v108, v109
	v_cvt_pk_bf16_f32 v126, v110, v111
	v_mul_f32_e32 v109, v109, v109
	v_fmac_f32_e32 v109, v108, v108
	v_cndmask_b32_e32 v108, v147, v126, vcc
	v_cndmask_b32_e32 v127, v93, v124, vcc
	v_cndmask_b32_e32 v93, v124, v93, vcc
	ds_bpermute_b32 v108, v143, v108
	ds_bpermute_b32 v124, v143, v127
	v_fmac_f32_e32 v109, v110, v110
	v_cndmask_b32_e32 v126, v126, v147, vcc
	v_fmac_f32_e32 v109, v111, v111
	v_add_f32_e32 v147, v125, v109
	s_waitcnt lgkmcnt(1)
	v_cndmask_b32_e32 v111, v126, v108, vcc
	v_cndmask_b32_e32 v109, v108, v126, vcc
	s_waitcnt lgkmcnt(0)
	v_cndmask_b32_e32 v110, v93, v124, vcc
	v_cndmask_b32_e32 v108, v124, v93, vcc
	s_waitcnt vmcnt(0)
	v_pk_add_f32 v[138:139], v[200:201], v[138:139]
	v_pk_add_f32 v[136:137], v[198:199], v[136:137]
	global_store_dwordx4 v[78:79], v[136:139], off offset:128
	global_load_dwordx4 v[148:151], v[94:95], off offset:192
	v_lshlrev_b64 v[94:95], 12, v[76:77]
	v_cvt_pk_bf16_f32 v93, v136, v137
	v_mul_f32_e32 v137, v137, v137
	v_lshl_add_u64 v[94:95], s[16:17], 0, v[94:95]
	v_fmac_f32_e32 v137, v136, v136
	v_lshl_add_u64 v[94:95], v[94:95], 0, s[22:23]
	v_fmac_f32_e32 v137, v138, v138
	v_lshl_add_u64 v[94:95], v[94:95], 0, v[134:135]
	v_fmac_f32_e32 v137, v139, v139
	v_cvt_pk_bf16_f32 v152, v138, v139
	s_waitcnt vmcnt(0)
	v_pk_add_f32 v[126:127], v[188:189], v[150:151]
	v_pk_add_f32 v[124:125], v[186:187], v[148:149]
	global_store_dwordx4 v[78:79], v[124:127], off offset:192
	v_cvt_pk_bf16_f32 v78, v124, v125
	global_store_dwordx4 v[94:95], v[108:111], off
	v_mul_f32_e32 v125, v125, v125
	v_fmac_f32_e32 v125, v124, v124
	v_fmac_f32_e32 v125, v126, v126
	v_fmac_f32_e32 v125, v127, v127
	v_add_f32_e32 v110, v147, v137
	v_add_f32_e32 v110, v110, v125
	ds_bpermute_b32 v124, v143, v110
	v_cvt_pk_bf16_f32 v79, v126, v127
	v_cndmask_b32_e32 v108, v152, v79, vcc
	v_cndmask_b32_e32 v109, v93, v78, vcc
	ds_bpermute_b32 v108, v143, v108
	v_cndmask_b32_e32 v93, v78, v93, vcc
	ds_bpermute_b32 v126, v143, v109
	s_waitcnt lgkmcnt(2)
	v_add_f32_e32 v78, v110, v124
	v_cndmask_b32_e32 v125, v79, v152, vcc
	ds_bpermute_b32 v79, v144, v78
	s_waitcnt lgkmcnt(2)
	v_cndmask_b32_e32 v111, v125, v108, vcc
	v_cndmask_b32_e32 v109, v108, v125, vcc
	s_waitcnt lgkmcnt(1)
	v_cndmask_b32_e32 v110, v93, v126, vcc
	v_cndmask_b32_e32 v108, v126, v93, vcc
	global_store_dwordx4 v[94:95], v[108:111], off offset:64
	s_and_saveexec_b64 s[44:45], s[8:9]
	s_cbranch_execz .LBB0_1180
	s_waitcnt lgkmcnt(0)
	v_add_f32_e32 v93, v78, v79
	v_lshlrev_b64 v[78:79], 7, v[76:77]
	v_lshl_add_u64 v[78:79], s[18:19], 0, v[78:79]
	s_lshl_b32 s0, s47, 2
	s_mov_b32 s1, s23
	v_lshl_add_u64 v[78:79], v[78:79], 0, s[0:1]
	s_lshl_b32 s0, s46, 2
	v_lshl_add_u64 v[78:79], v[78:79], 0, s[0:1]
	global_store_dword v[78:79], v93, off

.LBB0_1249:
	s_and_b32 s39, s38, 1
	s_xor_b32 s40, s39, 1
	s_lshl_b32 s41, s40, 14
	v_lshl_add_u64 v[150:151], v[138:139], 0, s[34:35]
	s_add_i32 s41, s36, s41
	v_lshl_add_u64 v[156:157], v[150:151], 0, 64
	s_mov_b32 m0, s41
	v_lshl_add_u64 v[158:159], v[150:151], 0, s[26:27]
	global_load_lds_dwordx4 v[156:157], off
	s_add_i32 m0, s41, 0x400
	v_lshl_add_u64 v[160:161], v[150:151], 0, s[28:29]
	s_lshl_b32 s40, s40, 13
	global_load_lds_dwordx4 v[158:159], off
	s_add_i32 m0, s41, 0x800
	v_lshl_add_u64 v[152:153], v[140:141], 0, s[34:35]
	v_lshl_add_u64 v[150:151], v[150:151], 0, s[30:31]
	s_add_i32 s40, s37, s40
	global_load_lds_dwordx4 v[160:161], off
	s_add_i32 m0, s41, 0xc00
	v_lshl_add_u64 v[162:163], v[152:153], 0, 64
	global_load_lds_dwordx4 v[150:151], off
	s_add_i32 m0, s40, 0x8000
	v_lshl_add_u64 v[152:153], v[152:153], 0, s[26:27]
	global_load_lds_dwordx4 v[162:163], off
	s_add_i32 m0, s40, 0x8400
	v_lshl_or_b32 v134, s39, 13, v137
	global_load_lds_dwordx4 v[152:153], off
	v_lshl_add_u32 v149, s39, 14, v148
	ds_read_b128 v[150:153], v134 offset:32768
	ds_read_b128 v[156:159], v134 offset:33792
	ds_read_b128 v[160:163], v134 offset:34816
	ds_read_b128 v[164:167], v134 offset:35840
	ds_read_b128 v[168:171], v149
	ds_read_b128 v[178:181], v149 offset:1024
	ds_read_b128 v[182:185], v149 offset:2048
	ds_read_b128 v[186:189], v149 offset:3072
	ds_read_b128 v[190:193], v149 offset:4096
	ds_read_b128 v[194:197], v149 offset:5120
	ds_read_b128 v[198:201], v149 offset:6144
	ds_read_b128 v[202:205], v149 offset:7168
	s_add_i32 s38, s38, 1
	s_setprio 1
	s_waitcnt lgkmcnt(0)
	v_mfma_f32_16x16x32_bf16 v[124:127], v[150:153], v[168:171], v[124:127]
	v_mfma_f32_16x16x32_bf16 v[120:123], v[150:153], v[178:181], v[120:123]
	v_mfma_f32_16x16x32_bf16 v[116:119], v[150:153], v[182:185], v[116:119]
	v_mfma_f32_16x16x32_bf16 v[112:115], v[150:153], v[186:189], v[112:115]
	v_mfma_f32_16x16x32_bf16 v[108:111], v[150:153], v[190:193], v[108:111]
	v_mfma_f32_16x16x32_bf16 v[104:107], v[150:153], v[194:197], v[104:107]
	v_mfma_f32_16x16x32_bf16 v[100:103], v[150:153], v[198:201], v[100:103]
	v_mfma_f32_16x16x32_bf16 v[96:99], v[150:153], v[202:205], v[96:99]
	v_mfma_f32_16x16x32_bf16 v[92:95], v[156:159], v[168:171], v[92:95]
	v_mfma_f32_16x16x32_bf16 v[88:91], v[156:159], v[178:181], v[88:91]
	v_mfma_f32_16x16x32_bf16 v[84:87], v[156:159], v[182:185], v[84:87]
	v_mfma_f32_16x16x32_bf16 v[80:83], v[156:159], v[186:189], v[80:83]
	v_mfma_f32_16x16x32_bf16 v[76:79], v[156:159], v[190:193], v[76:79]
	v_mfma_f32_16x16x32_bf16 v[72:75], v[156:159], v[194:197], v[72:75]
	v_mfma_f32_16x16x32_bf16 v[68:71], v[156:159], v[198:201], v[68:71]
	v_mfma_f32_16x16x32_bf16 v[64:67], v[156:159], v[202:205], v[64:67]
	v_mfma_f32_16x16x32_bf16 v[60:63], v[160:163], v[168:171], v[60:63]
	v_mfma_f32_16x16x32_bf16 v[56:59], v[160:163], v[178:181], v[56:59]
	v_mfma_f32_16x16x32_bf16 v[52:55], v[160:163], v[182:185], v[52:55]
	v_mfma_f32_16x16x32_bf16 v[48:51], v[160:163], v[186:189], v[48:51]
	v_mfma_f32_16x16x32_bf16 v[44:47], v[160:163], v[190:193], v[44:47]
	v_mfma_f32_16x16x32_bf16 v[40:43], v[160:163], v[194:197], v[40:43]
	v_mfma_f32_16x16x32_bf16 v[36:39], v[160:163], v[198:201], v[36:39]
	v_mfma_f32_16x16x32_bf16 v[32:35], v[160:163], v[202:205], v[32:35]
	v_mfma_f32_16x16x32_bf16 v[28:31], v[164:167], v[168:171], v[28:31]
	v_mfma_f32_16x16x32_bf16 v[24:27], v[164:167], v[178:181], v[24:27]
	v_mfma_f32_16x16x32_bf16 v[20:23], v[164:167], v[182:185], v[20:23]
	v_mfma_f32_16x16x32_bf16 v[16:19], v[164:167], v[186:189], v[16:19]
	v_mfma_f32_16x16x32_bf16 v[12:15], v[164:167], v[190:193], v[12:15]
	v_mfma_f32_16x16x32_bf16 v[8:11], v[164:167], v[194:197], v[8:11]
	v_mfma_f32_16x16x32_bf16 v[4:7], v[164:167], v[198:201], v[4:7]
	v_mfma_f32_16x16x32_bf16 v[0:3], v[164:167], v[202:205], v[0:3]
	s_setprio 0
	s_add_u32 s34, s34, 64
	s_addc_u32 s35, s35, 0
	s_cmpk_lg_i32 s34, 0xfc0
	s_waitcnt vmcnt(0)
	s_barrier
	s_cbranch_scc1 .LBB0_1249
	ds_read_b128 v[138:141], v148 offset:23552
	ds_read_b128 v[150:153], v148 offset:22528
	ds_read_b128 v[156:159], v148 offset:21504
	ds_read_b128 v[160:163], v148 offset:20480
	ds_read_b128 v[164:167], v148 offset:19456
	ds_read_b128 v[168:171], v148 offset:18432
	ds_read_b128 v[178:181], v148 offset:17408
	ds_read_b128 v[182:185], v148 offset:16384
	ds_read_b128 v[186:189], v137 offset:44032
	ds_read_b128 v[190:193], v137 offset:43008
	ds_read_b128 v[194:197], v137 offset:41984
	ds_read_b128 v[198:201], v137 offset:40960
	s_setprio 1
	s_waitcnt lgkmcnt(0)
	v_mfma_f32_16x16x32_bf16 v[124:127], v[198:201], v[182:185], v[124:127]
	v_mfma_f32_16x16x32_bf16 v[120:123], v[198:201], v[178:181], v[120:123]
	v_mfma_f32_16x16x32_bf16 v[116:119], v[198:201], v[168:171], v[116:119]
	v_mfma_f32_16x16x32_bf16 v[112:115], v[198:201], v[164:167], v[112:115]
	v_mfma_f32_16x16x32_bf16 v[108:111], v[198:201], v[160:163], v[108:111]
	v_mfma_f32_16x16x32_bf16 v[104:107], v[198:201], v[156:159], v[104:107]
	v_mfma_f32_16x16x32_bf16 v[100:103], v[198:201], v[150:153], v[100:103]
	v_mfma_f32_16x16x32_bf16 v[96:99], v[198:201], v[138:141], v[96:99]
	v_mfma_f32_16x16x32_bf16 v[92:95], v[194:197], v[182:185], v[92:95]
	v_mfma_f32_16x16x32_bf16 v[88:91], v[194:197], v[178:181], v[88:91]
	v_mfma_f32_16x16x32_bf16 v[84:87], v[194:197], v[168:171], v[84:87]
	v_mfma_f32_16x16x32_bf16 v[80:83], v[194:197], v[164:167], v[80:83]
	v_mfma_f32_16x16x32_bf16 v[76:79], v[194:197], v[160:163], v[76:79]
	v_mfma_f32_16x16x32_bf16 v[72:75], v[194:197], v[156:159], v[72:75]
	v_mfma_f32_16x16x32_bf16 v[68:71], v[194:197], v[150:153], v[68:71]
	v_mfma_f32_16x16x32_bf16 v[64:67], v[194:197], v[138:141], v[64:67]
	v_mfma_f32_16x16x32_bf16 v[60:63], v[190:193], v[182:185], v[60:63]
	v_mfma_f32_16x16x32_bf16 v[56:59], v[190:193], v[178:181], v[56:59]
	v_mfma_f32_16x16x32_bf16 v[52:55], v[190:193], v[168:171], v[52:55]
	v_mfma_f32_16x16x32_bf16 v[48:51], v[190:193], v[164:167], v[48:51]
	v_mfma_f32_16x16x32_bf16 v[44:47], v[190:193], v[160:163], v[44:47]
	v_mfma_f32_16x16x32_bf16 v[40:43], v[190:193], v[156:159], v[40:43]
	v_mfma_f32_16x16x32_bf16 v[36:39], v[190:193], v[150:153], v[36:39]
	v_mfma_f32_16x16x32_bf16 v[32:35], v[190:193], v[138:141], v[32:35]
	v_mfma_f32_16x16x32_bf16 v[28:31], v[186:189], v[182:185], v[28:31]
	v_mfma_f32_16x16x32_bf16 v[24:27], v[186:189], v[178:181], v[24:27]
	v_mfma_f32_16x16x32_bf16 v[20:23], v[186:189], v[168:171], v[20:23]
	v_mfma_f32_16x16x32_bf16 v[164:167], v[186:189], v[164:167], v[16:19]
	v_mfma_f32_16x16x32_bf16 v[12:15], v[186:189], v[160:163], v[12:15]
	v_mfma_f32_16x16x32_bf16 v[8:11], v[186:189], v[156:159], v[8:11]
	v_mfma_f32_16x16x32_bf16 v[4:7], v[186:189], v[150:153], v[4:7]
	v_mfma_f32_16x16x32_bf16 v[0:3], v[186:189], v[138:141], v[0:3]
	s_setprio 0
	v_cvt_pk_bf16_f32 v124, v124, v125
	v_cvt_pk_bf16_f32 v125, v126, v127
	v_cvt_pk_bf16_f32 v92, v92, v93
	v_cvt_pk_bf16_f32 v93, v94, v95
	v_cndmask_b32_e32 v18, v125, v93, vcc
	v_cndmask_b32_e32 v19, v124, v92, vcc
	s_lshl_b32 s33, s33, 8
	ds_bpermute_b32 v126, v145, v18
	ds_bpermute_b32 v127, v145, v19
	s_add_i32 s16, s16, s33
	v_or_b32_e32 v16, s16, v129
	v_ashrrev_i32_e32 v17, 31, v16
	v_lshlrev_b64 v[18:19], 12, v[16:17]
	v_cndmask_b32_e32 v17, v92, v124, vcc
	v_cndmask_b32_e32 v92, v93, v125, vcc
	s_waitcnt lgkmcnt(1)
	v_cndmask_b32_e32 v95, v92, v126, vcc
	s_waitcnt lgkmcnt(0)
	v_cndmask_b32_e32 v94, v17, v127, vcc
	v_cndmask_b32_e32 v93, v126, v92, vcc
	v_cndmask_b32_e32 v92, v127, v17, vcc
	v_cvt_pk_bf16_f32 v17, v60, v61
	v_cvt_pk_bf16_f32 v60, v62, v63
	v_cvt_pk_bf16_f32 v28, v28, v29
	v_cvt_pk_bf16_f32 v29, v30, v31
	v_cndmask_b32_e32 v30, v60, v29, vcc
	v_cndmask_b32_e32 v31, v17, v28, vcc
	ds_bpermute_b32 v61, v145, v30
	ds_bpermute_b32 v62, v145, v31
	s_lshl_b32 s0, s0, 8
	s_lshl_b32 s1, s1, 7
	v_lshl_add_u64 v[18:19], s[12:13], 0, v[18:19]
	s_or_b32 s16, s1, s0
	v_lshl_add_u64 v[18:19], v[18:19], 0, s[16:17]
	v_mov_b32_e32 v137, v135
	v_cndmask_b32_e32 v17, v28, v17, vcc
	v_cndmask_b32_e32 v28, v29, v60, vcc
	v_lshl_add_u64 v[18:19], v[18:19], 0, v[136:137]
	s_waitcnt lgkmcnt(1)
	v_cndmask_b32_e32 v31, v28, v61, vcc
	s_waitcnt lgkmcnt(0)
	v_cndmask_b32_e32 v30, v17, v62, vcc
	v_cndmask_b32_e32 v29, v61, v28, vcc
	v_cndmask_b32_e32 v28, v62, v17, vcc
	s_barrier
	global_store_dwordx4 v[18:19], v[28:31], off offset:64
	v_cvt_pk_bf16_f32 v17, v120, v121
	v_cvt_pk_bf16_f32 v24, v24, v25
	v_cvt_pk_bf16_f32 v28, v122, v123
	v_cvt_pk_bf16_f32 v29, v88, v89
	v_cvt_pk_bf16_f32 v30, v90, v91
	v_cndmask_b32_e32 v31, v28, v30, vcc
	v_cndmask_b32_e32 v60, v17, v29, vcc
	ds_bpermute_b32 v61, v145, v31
	ds_bpermute_b32 v60, v145, v60
	v_cndmask_b32_e32 v17, v29, v17, vcc
	v_cndmask_b32_e32 v28, v30, v28, vcc
	v_cvt_pk_bf16_f32 v25, v26, v27
	s_waitcnt lgkmcnt(1)
	v_cndmask_b32_e32 v31, v28, v61, vcc
	s_waitcnt lgkmcnt(0)
	v_cndmask_b32_e32 v30, v17, v60, vcc
	v_cndmask_b32_e32 v29, v61, v28, vcc
	v_cndmask_b32_e32 v28, v60, v17, vcc
	v_cvt_pk_bf16_f32 v17, v56, v57
	v_cvt_pk_bf16_f32 v56, v58, v59
	v_cndmask_b32_e32 v26, v56, v25, vcc
	v_cndmask_b32_e32 v27, v17, v24, vcc
	global_store_dwordx4 v[18:19], v[92:95], off
	v_or_b32_e32 v18, 16, v16
	ds_bpermute_b32 v57, v145, v26
	ds_bpermute_b32 v58, v145, v27
	v_ashrrev_i32_e32 v19, 31, v18
	v_lshlrev_b64 v[18:19], 12, v[18:19]
	v_lshl_add_u64 v[18:19], s[12:13], 0, v[18:19]
	v_lshl_add_u64 v[18:19], v[18:19], 0, s[16:17]
	v_cndmask_b32_e32 v17, v24, v17, vcc
	v_cndmask_b32_e32 v24, v25, v56, vcc
	v_lshl_add_u64 v[18:19], v[18:19], 0, v[136:137]
	s_waitcnt lgkmcnt(1)
	v_cndmask_b32_e32 v27, v24, v57, vcc
	s_waitcnt lgkmcnt(0)
	v_cndmask_b32_e32 v26, v17, v58, vcc
	v_cndmask_b32_e32 v25, v57, v24, vcc
	v_cndmask_b32_e32 v24, v58, v17, vcc
	global_store_dwordx4 v[18:19], v[24:27], off offset:64
	v_cvt_pk_bf16_f32 v17, v116, v117
	global_store_dwordx4 v[18:19], v[28:31], off
	v_cvt_pk_bf16_f32 v24, v118, v119
	v_cvt_pk_bf16_f32 v25, v84, v85
	v_cvt_pk_bf16_f32 v26, v86, v87
	v_cndmask_b32_e32 v27, v24, v26, vcc
	v_cndmask_b32_e32 v28, v17, v25, vcc
	v_or_b32_e32 v18, 32, v16
	ds_bpermute_b32 v29, v145, v27
	ds_bpermute_b32 v28, v145, v28
	v_ashrrev_i32_e32 v19, 31, v18
	v_lshlrev_b64 v[18:19], 12, v[18:19]
	v_lshl_add_u64 v[18:19], s[12:13], 0, v[18:19]
	v_cndmask_b32_e32 v17, v25, v17, vcc
	v_cndmask_b32_e32 v24, v26, v24, vcc
	v_lshl_add_u64 v[18:19], v[18:19], 0, s[16:17]
	s_waitcnt lgkmcnt(1)
	v_cndmask_b32_e32 v27, v24, v29, vcc
	s_waitcnt lgkmcnt(0)
	v_cndmask_b32_e32 v26, v17, v28, vcc
	v_cndmask_b32_e32 v25, v29, v24, vcc
	v_cndmask_b32_e32 v24, v28, v17, vcc
	v_lshl_add_u64 v[28:29], v[18:19], 0, v[136:137]
	v_cvt_pk_bf16_f32 v17, v52, v53
	v_cvt_pk_bf16_f32 v18, v54, v55
	v_cvt_pk_bf16_f32 v19, v20, v21
	v_cvt_pk_bf16_f32 v20, v22, v23
	v_cndmask_b32_e32 v21, v18, v20, vcc
	v_cndmask_b32_e32 v22, v17, v19, vcc
	ds_bpermute_b32 v23, v145, v21
	ds_bpermute_b32 v22, v145, v22
	v_cndmask_b32_e32 v17, v19, v17, vcc
	v_cndmask_b32_e32 v18, v20, v18, vcc
	global_store_dwordx4 v[28:29], v[24:27], off
	s_waitcnt lgkmcnt(1)
	v_cndmask_b32_e32 v21, v18, v23, vcc
	s_waitcnt lgkmcnt(0)
	v_cndmask_b32_e32 v20, v17, v22, vcc
	v_cndmask_b32_e32 v19, v23, v18, vcc
	v_cndmask_b32_e32 v18, v22, v17, vcc
	global_store_dwordx4 v[28:29], v[18:21], off offset:64
	v_cvt_pk_bf16_f32 v17, v112, v113
	v_cvt_pk_bf16_f32 v24, v82, v83
	v_cvt_pk_bf16_f32 v20, v114, v115
	v_cvt_pk_bf16_f32 v21, v80, v81
	v_cndmask_b32_e32 v22, v20, v24, vcc
	v_cndmask_b32_e32 v23, v17, v21, vcc
	ds_bpermute_b32 v25, v145, v22
	ds_bpermute_b32 v26, v145, v23
	v_or_b32_e32 v18, 48, v16
	v_ashrrev_i32_e32 v19, 31, v18
	v_lshlrev_b64 v[22:23], 12, v[18:19]
	v_cndmask_b32_e32 v17, v21, v17, vcc
	v_cndmask_b32_e32 v18, v24, v20, vcc
	s_waitcnt lgkmcnt(1)
	v_cndmask_b32_e32 v21, v18, v25, vcc
	s_waitcnt lgkmcnt(0)
	v_cndmask_b32_e32 v20, v17, v26, vcc
	v_cndmask_b32_e32 v19, v25, v18, vcc
	v_cndmask_b32_e32 v18, v26, v17, vcc
	v_cvt_pk_bf16_f32 v17, v48, v49
	v_cvt_pk_bf16_f32 v24, v50, v51
	v_cvt_pk_bf16_f32 v25, v164, v165
	v_cvt_pk_bf16_f32 v26, v166, v167
	v_cndmask_b32_e32 v27, v24, v26, vcc
	v_cndmask_b32_e32 v28, v17, v25, vcc
	ds_bpermute_b32 v27, v145, v27
	ds_bpermute_b32 v28, v145, v28
	v_lshl_add_u64 v[22:23], s[12:13], 0, v[22:23]
	v_lshl_add_u64 v[22:23], v[22:23], 0, s[16:17]
	v_lshl_add_u64 v[22:23], v[22:23], 0, v[136:137]
	global_store_dwordx4 v[22:23], v[18:21], off
	v_cndmask_b32_e32 v17, v25, v17, vcc
	v_cvt_pk_bf16_f32 v12, v12, v13
	v_cndmask_b32_e32 v18, v26, v24, vcc
	s_waitcnt lgkmcnt(1)
	v_cndmask_b32_e32 v21, v18, v27, vcc
	s_waitcnt lgkmcnt(0)
	v_cndmask_b32_e32 v20, v17, v28, vcc
	v_cndmask_b32_e32 v19, v27, v18, vcc
	v_cndmask_b32_e32 v18, v28, v17, vcc
	global_store_dwordx4 v[22:23], v[18:21], off offset:64
	v_cvt_pk_bf16_f32 v17, v108, v109
	v_cvt_pk_bf16_f32 v24, v78, v79
	v_cvt_pk_bf16_f32 v20, v110, v111
	v_cvt_pk_bf16_f32 v21, v76, v77
	v_cndmask_b32_e32 v22, v20, v24, vcc
	v_cndmask_b32_e32 v23, v17, v21, vcc
	ds_bpermute_b32 v25, v145, v22
	ds_bpermute_b32 v26, v145, v23
	v_or_b32_e32 v18, 64, v16
	v_ashrrev_i32_e32 v19, 31, v18
	v_lshlrev_b64 v[22:23], 12, v[18:19]
	v_cndmask_b32_e32 v17, v21, v17, vcc
	v_cndmask_b32_e32 v18, v24, v20, vcc
	s_waitcnt lgkmcnt(1)
	v_cndmask_b32_e32 v21, v18, v25, vcc
	s_waitcnt lgkmcnt(0)
	v_cndmask_b32_e32 v20, v17, v26, vcc
	v_cndmask_b32_e32 v19, v25, v18, vcc
	v_cndmask_b32_e32 v18, v26, v17, vcc
	v_cvt_pk_bf16_f32 v17, v44, v45
	v_cvt_pk_bf16_f32 v24, v46, v47
	v_cvt_pk_bf16_f32 v13, v14, v15
	v_cndmask_b32_e32 v14, v24, v13, vcc
	v_cndmask_b32_e32 v15, v17, v12, vcc
	ds_bpermute_b32 v25, v145, v14
	ds_bpermute_b32 v26, v145, v15
	v_lshl_add_u64 v[22:23], s[12:13], 0, v[22:23]
	v_lshl_add_u64 v[22:23], v[22:23], 0, s[16:17]
	v_cndmask_b32_e32 v12, v12, v17, vcc
	v_cndmask_b32_e32 v13, v13, v24, vcc
	v_lshl_add_u64 v[22:23], v[22:23], 0, v[136:137]
	s_waitcnt lgkmcnt(1)
	v_cndmask_b32_e32 v15, v13, v25, vcc
	s_waitcnt lgkmcnt(0)
	v_cndmask_b32_e32 v14, v12, v26, vcc
	v_cndmask_b32_e32 v13, v25, v13, vcc
	v_cndmask_b32_e32 v12, v26, v12, vcc
	global_store_dwordx4 v[22:23], v[18:21], off
	global_store_dwordx4 v[22:23], v[12:15], off offset:64
	v_cvt_pk_bf16_f32 v17, v72, v73
	v_cvt_pk_bf16_f32 v20, v74, v75
	v_cvt_pk_bf16_f32 v14, v104, v105
	v_cvt_pk_bf16_f32 v15, v106, v107
	v_cndmask_b32_e32 v18, v15, v20, vcc
	v_cndmask_b32_e32 v19, v14, v17, vcc
	ds_bpermute_b32 v21, v145, v18
	ds_bpermute_b32 v22, v145, v19
	v_or_b32_e32 v12, 0x50, v16
	v_ashrrev_i32_e32 v13, 31, v12
	v_lshlrev_b64 v[18:19], 12, v[12:13]
	v_cndmask_b32_e32 v12, v17, v14, vcc
	v_cndmask_b32_e32 v13, v20, v15, vcc
	v_cvt_pk_bf16_f32 v17, v40, v41
	v_cvt_pk_bf16_f32 v20, v42, v43
	v_cvt_pk_bf16_f32 v8, v8, v9
	v_cvt_pk_bf16_f32 v9, v10, v11
	v_cndmask_b32_e32 v10, v20, v9, vcc
	v_cndmask_b32_e32 v11, v17, v8, vcc
	s_waitcnt lgkmcnt(1)
	v_cndmask_b32_e32 v15, v13, v21, vcc
	s_waitcnt lgkmcnt(0)
	v_cndmask_b32_e32 v14, v12, v22, vcc
	v_cndmask_b32_e32 v13, v21, v13, vcc
	v_cndmask_b32_e32 v12, v22, v12, vcc
	ds_bpermute_b32 v21, v145, v10
	ds_bpermute_b32 v22, v145, v11
	v_lshl_add_u64 v[18:19], s[12:13], 0, v[18:19]
	v_lshl_add_u64 v[18:19], v[18:19], 0, s[16:17]
	v_cndmask_b32_e32 v8, v8, v17, vcc
	v_cndmask_b32_e32 v9, v9, v20, vcc
	v_lshl_add_u64 v[18:19], v[18:19], 0, v[136:137]
	s_waitcnt lgkmcnt(1)
	v_cndmask_b32_e32 v11, v9, v21, vcc
	s_waitcnt lgkmcnt(0)
	v_cndmask_b32_e32 v10, v8, v22, vcc
	v_cndmask_b32_e32 v9, v21, v9, vcc
	v_cndmask_b32_e32 v8, v22, v8, vcc
	global_store_dwordx4 v[18:19], v[12:15], off
	global_store_dwordx4 v[18:19], v[8:11], off offset:64
	v_cvt_pk_bf16_f32 v4, v4, v5
	v_cvt_pk_bf16_f32 v14, v68, v69
	v_cvt_pk_bf16_f32 v10, v100, v101
	v_cvt_pk_bf16_f32 v11, v102, v103
	v_cvt_pk_bf16_f32 v15, v70, v71
	v_cndmask_b32_e32 v12, v11, v15, vcc
	v_cndmask_b32_e32 v13, v10, v14, vcc
	ds_bpermute_b32 v17, v145, v12
	ds_bpermute_b32 v18, v145, v13
	v_or_b32_e32 v8, 0x60, v16
	v_ashrrev_i32_e32 v9, 31, v8
	v_lshlrev_b64 v[12:13], 12, v[8:9]
	v_cndmask_b32_e32 v8, v14, v10, vcc
	v_cndmask_b32_e32 v9, v15, v11, vcc
	v_cvt_pk_bf16_f32 v14, v36, v37
	v_cvt_pk_bf16_f32 v15, v38, v39
	v_cvt_pk_bf16_f32 v5, v6, v7
	v_cndmask_b32_e32 v6, v15, v5, vcc
	v_cndmask_b32_e32 v7, v14, v4, vcc
	s_waitcnt lgkmcnt(1)
	v_cndmask_b32_e32 v11, v9, v17, vcc
	s_waitcnt lgkmcnt(0)
	v_cndmask_b32_e32 v10, v8, v18, vcc
	v_cndmask_b32_e32 v9, v17, v9, vcc
	v_cndmask_b32_e32 v8, v18, v8, vcc
	ds_bpermute_b32 v17, v145, v6
	ds_bpermute_b32 v18, v145, v7
	v_lshl_add_u64 v[12:13], s[12:13], 0, v[12:13]
	v_lshl_add_u64 v[12:13], v[12:13], 0, s[16:17]
	v_cndmask_b32_e32 v4, v4, v14, vcc
	v_cndmask_b32_e32 v5, v5, v15, vcc
	v_lshl_add_u64 v[12:13], v[12:13], 0, v[136:137]
	s_waitcnt lgkmcnt(1)
	v_cndmask_b32_e32 v7, v5, v17, vcc
	s_waitcnt lgkmcnt(0)
	v_cndmask_b32_e32 v6, v4, v18, vcc
	v_cndmask_b32_e32 v5, v17, v5, vcc
	v_cndmask_b32_e32 v4, v18, v4, vcc
	global_store_dwordx4 v[12:13], v[8:11], off
	global_store_dwordx4 v[12:13], v[4:7], off offset:64
	v_cvt_pk_bf16_f32 v0, v0, v1
	v_cvt_pk_bf16_f32 v10, v64, v65
	v_cvt_pk_bf16_f32 v6, v96, v97
	v_cvt_pk_bf16_f32 v7, v98, v99
	v_cvt_pk_bf16_f32 v11, v66, v67
	v_cndmask_b32_e32 v8, v7, v11, vcc
	v_cndmask_b32_e32 v9, v6, v10, vcc
	ds_bpermute_b32 v12, v145, v8
	ds_bpermute_b32 v13, v145, v9
	v_or_b32_e32 v4, 0x70, v16
	v_ashrrev_i32_e32 v5, 31, v4
	v_lshlrev_b64 v[8:9], 12, v[4:5]
	v_cndmask_b32_e32 v4, v10, v6, vcc
	v_cndmask_b32_e32 v5, v11, v7, vcc
	v_cvt_pk_bf16_f32 v10, v32, v33
	v_cvt_pk_bf16_f32 v11, v34, v35
	v_cvt_pk_bf16_f32 v1, v2, v3
	v_cndmask_b32_e32 v2, v11, v1, vcc
	v_cndmask_b32_e32 v3, v10, v0, vcc
	s_waitcnt lgkmcnt(1)
	v_cndmask_b32_e32 v7, v5, v12, vcc
	s_waitcnt lgkmcnt(0)
	v_cndmask_b32_e32 v6, v4, v13, vcc
	v_cndmask_b32_e32 v5, v12, v5, vcc
	v_cndmask_b32_e32 v4, v13, v4, vcc
	ds_bpermute_b32 v12, v145, v2
	ds_bpermute_b32 v13, v145, v3
	v_lshl_add_u64 v[8:9], s[12:13], 0, v[8:9]
	v_lshl_add_u64 v[8:9], v[8:9], 0, s[16:17]
	v_cndmask_b32_e32 v0, v0, v10, vcc
	v_cndmask_b32_e32 v1, v1, v11, vcc
	s_add_i32 s7, s7, s89
	s_xor_b64 s[8:9], s[8:9], s[18:19]
	v_lshl_add_u64 v[8:9], v[8:9], 0, v[136:137]
	s_waitcnt lgkmcnt(1)
	v_cndmask_b32_e32 v3, v1, v12, vcc
	s_waitcnt lgkmcnt(0)
	v_cndmask_b32_e32 v2, v0, v13, vcc
	v_cndmask_b32_e32 v1, v12, v1, vcc
	v_cndmask_b32_e32 v0, v13, v0, vcc
	s_cmpk_gt_u32 s7, 0xff
	global_store_dwordx4 v[8:9], v[4:7], off
	global_store_dwordx4 v[8:9], v[0:3], off offset:64
	s_cbranch_scc0 .LBB0_1248
